# LDS-DMA loops: fragment reads also software-pipelined across the MFMAs (one k-half / two k-steps ahead) with exact counted waits
# speedup vs baseline: 1.0111x; 1.0036x over previous
.Lf2_stage0:
	ds_read_b128 v[66:69], v130 offset:0
	ds_read_b128 v[74:77], v134 offset:16384
	ds_read_b128 v[78:81], v134 offset:20480
	ds_read_b128 v[70:73], v130 offset:4096
	ds_read_b128 v[82:85], v131 offset:0
	ds_read_b128 v[90:93], v135 offset:16384
	ds_read_b128 v[94:97], v135 offset:20480
	ds_read_b128 v[86:89], v131 offset:4096
	s_cmp_ge_u32 s22, 43
	s_cbranch_scc1 .Lf2_nl0
	s_waitcnt lgkmcnt(6)
	s_add_u32 m0, s38, 0x8000
	v_mfma_f32_32x32x16_f16 v[50:65], v[66:69], v[74:77], v[50:65]
	global_load_lds_dwordx4 v152, s[10:11]
	ds_read_b128 v[98:101], v132 offset:0
	s_waitcnt lgkmcnt(6)
	s_add_u32 m0, s38, 0xc000
	v_mfma_f32_32x32x16_f16 v[34:49], v[66:69], v[78:81], v[34:49]
	global_load_lds_dwordx4 v152, s[8:9]
	ds_read_b128 v[106:109], v136 offset:16384
	s_waitcnt lgkmcnt(6)
	s_add_u32 m0, s38, 0x9000
	v_mfma_f32_32x32x16_f16 v[18:33], v[70:73], v[74:77], v[18:33]
	global_load_lds_dwordx4 v150, s[10:11]
	ds_read_b128 v[110:113], v136 offset:20480
	s_add_u32 m0, s38, 0xd000
	v_mfma_f32_32x32x16_f16 v[2:17], v[70:73], v[78:81], v[2:17]
	global_load_lds_dwordx4 v150, s[8:9]
	ds_read_b128 v[102:105], v132 offset:4096
	s_waitcnt lgkmcnt(6)
	s_add_u32 m0, s38, 0xa000
	v_mfma_f32_32x32x16_f16 v[50:65], v[82:85], v[90:93], v[50:65]
	global_load_lds_dwordx4 v148, s[10:11]
	ds_read_b128 v[114:117], v133 offset:0
	s_waitcnt lgkmcnt(6)
	s_add_u32 m0, s38, 0xe000
	v_mfma_f32_32x32x16_f16 v[34:49], v[82:85], v[94:97], v[34:49]
	global_load_lds_dwordx4 v148, s[8:9]
	ds_read_b128 v[122:125], v137 offset:16384
	s_waitcnt lgkmcnt(6)
	s_add_u32 m0, s38, 0xb000
	v_mfma_f32_32x32x16_f16 v[18:33], v[86:89], v[90:93], v[18:33]
	global_load_lds_dwordx4 v146, s[10:11]
	ds_read_b128 v[126:129], v137 offset:20480
	s_add_u32 m0, s38, 0xf000
	v_mfma_f32_32x32x16_f16 v[2:17], v[86:89], v[94:97], v[2:17]
	global_load_lds_dwordx4 v146, s[8:9]
	ds_read_b128 v[118:121], v133 offset:4096
	s_add_u32 s8, s8, 0x80
	s_addc_u32 s9, s9, 0
	s_add_u32 s10, s10, 0x80
	s_addc_u32 s11, s11, 0
	s_branch .Lf2_dd0
.Lf2_nl0:
	s_waitcnt lgkmcnt(6)
	v_mfma_f32_32x32x16_f16 v[50:65], v[66:69], v[74:77], v[50:65]
	ds_read_b128 v[98:101], v132 offset:0
	s_waitcnt lgkmcnt(6)
	v_mfma_f32_32x32x16_f16 v[34:49], v[66:69], v[78:81], v[34:49]
	ds_read_b128 v[106:109], v136 offset:16384
	s_waitcnt lgkmcnt(6)
	v_mfma_f32_32x32x16_f16 v[18:33], v[70:73], v[74:77], v[18:33]
	ds_read_b128 v[110:113], v136 offset:20480
	v_mfma_f32_32x32x16_f16 v[2:17], v[70:73], v[78:81], v[2:17]
	ds_read_b128 v[102:105], v132 offset:4096
	s_waitcnt lgkmcnt(6)
	v_mfma_f32_32x32x16_f16 v[50:65], v[82:85], v[90:93], v[50:65]
	ds_read_b128 v[114:117], v133 offset:0
	s_waitcnt lgkmcnt(6)
	v_mfma_f32_32x32x16_f16 v[34:49], v[82:85], v[94:97], v[34:49]
	ds_read_b128 v[122:125], v137 offset:16384
	s_waitcnt lgkmcnt(6)
	v_mfma_f32_32x32x16_f16 v[18:33], v[86:89], v[90:93], v[18:33]
	ds_read_b128 v[126:129], v137 offset:20480
	v_mfma_f32_32x32x16_f16 v[2:17], v[86:89], v[94:97], v[2:17]
	ds_read_b128 v[118:121], v133 offset:4096

.Lf2_stage1:
	ds_read_b128 v[66:69], v130 offset:32768
	ds_read_b128 v[74:77], v134 offset:49152
	ds_read_b128 v[78:81], v134 offset:53248
	ds_read_b128 v[70:73], v130 offset:36864
	ds_read_b128 v[82:85], v131 offset:32768
	ds_read_b128 v[90:93], v135 offset:49152
	ds_read_b128 v[94:97], v135 offset:53248
	ds_read_b128 v[86:89], v131 offset:36864
	s_cmp_ge_u32 s22, 43
	s_cbranch_scc1 .Lf2_nl1
	s_waitcnt lgkmcnt(6)
	s_add_u32 m0, s38, 0x0
	v_mfma_f32_32x32x16_f16 v[50:65], v[66:69], v[74:77], v[50:65]
	global_load_lds_dwordx4 v152, s[10:11]
	ds_read_b128 v[98:101], v132 offset:32768
	s_waitcnt lgkmcnt(6)
	s_add_u32 m0, s38, 0x4000
	v_mfma_f32_32x32x16_f16 v[34:49], v[66:69], v[78:81], v[34:49]
	global_load_lds_dwordx4 v152, s[8:9]
	ds_read_b128 v[106:109], v136 offset:49152
	s_waitcnt lgkmcnt(6)
	s_add_u32 m0, s38, 0x1000
	v_mfma_f32_32x32x16_f16 v[18:33], v[70:73], v[74:77], v[18:33]
	global_load_lds_dwordx4 v150, s[10:11]
	ds_read_b128 v[110:113], v136 offset:53248
	s_add_u32 m0, s38, 0x5000
	v_mfma_f32_32x32x16_f16 v[2:17], v[70:73], v[78:81], v[2:17]
	global_load_lds_dwordx4 v150, s[8:9]
	ds_read_b128 v[102:105], v132 offset:36864
	s_waitcnt lgkmcnt(6)
	s_add_u32 m0, s38, 0x2000
	v_mfma_f32_32x32x16_f16 v[50:65], v[82:85], v[90:93], v[50:65]
	global_load_lds_dwordx4 v148, s[10:11]
	ds_read_b128 v[114:117], v133 offset:32768
	s_waitcnt lgkmcnt(6)
	s_add_u32 m0, s38, 0x6000
	v_mfma_f32_32x32x16_f16 v[34:49], v[82:85], v[94:97], v[34:49]
	global_load_lds_dwordx4 v148, s[8:9]
	ds_read_b128 v[122:125], v137 offset:49152
	s_waitcnt lgkmcnt(6)
	s_add_u32 m0, s38, 0x3000
	v_mfma_f32_32x32x16_f16 v[18:33], v[86:89], v[90:93], v[18:33]
	global_load_lds_dwordx4 v146, s[10:11]
	ds_read_b128 v[126:129], v137 offset:53248
	s_add_u32 m0, s38, 0x7000
	v_mfma_f32_32x32x16_f16 v[2:17], v[86:89], v[94:97], v[2:17]
	global_load_lds_dwordx4 v146, s[8:9]
	ds_read_b128 v[118:121], v133 offset:36864
	s_add_u32 s8, s8, 0x80
	s_addc_u32 s9, s9, 0
	s_add_u32 s10, s10, 0x80
	s_addc_u32 s11, s11, 0
	s_branch .Lf2_dd1
.Lf2_nl1:
	s_waitcnt lgkmcnt(6)
	v_mfma_f32_32x32x16_f16 v[50:65], v[66:69], v[74:77], v[50:65]
	ds_read_b128 v[98:101], v132 offset:32768
	s_waitcnt lgkmcnt(6)
	v_mfma_f32_32x32x16_f16 v[34:49], v[66:69], v[78:81], v[34:49]
	ds_read_b128 v[106:109], v136 offset:49152
	s_waitcnt lgkmcnt(6)
	v_mfma_f32_32x32x16_f16 v[18:33], v[70:73], v[74:77], v[18:33]
	ds_read_b128 v[110:113], v136 offset:53248
	v_mfma_f32_32x32x16_f16 v[2:17], v[70:73], v[78:81], v[2:17]
	ds_read_b128 v[102:105], v132 offset:36864
	s_waitcnt lgkmcnt(6)
	v_mfma_f32_32x32x16_f16 v[50:65], v[82:85], v[90:93], v[50:65]
	ds_read_b128 v[114:117], v133 offset:32768
	s_waitcnt lgkmcnt(6)
	v_mfma_f32_32x32x16_f16 v[34:49], v[82:85], v[94:97], v[34:49]
	ds_read_b128 v[122:125], v137 offset:49152
	s_waitcnt lgkmcnt(6)
	v_mfma_f32_32x32x16_f16 v[18:33], v[86:89], v[90:93], v[18:33]
	ds_read_b128 v[126:129], v137 offset:53248
	v_mfma_f32_32x32x16_f16 v[2:17], v[86:89], v[94:97], v[2:17]
	ds_read_b128 v[118:121], v133 offset:36864

.Lfg_stage0:
	ds_read_b128 v[178:181], v130 offset:0
	ds_read_b128 v[194:197], v132 offset:16384
	ds_read_b128 v[198:201], v132 offset:18432
	ds_read_b128 v[182:185], v130 offset:2048
	ds_read_b128 v[186:189], v130 offset:4096
	ds_read_b128 v[190:193], v130 offset:6144
	s_cmp_ge_u32 s13, 31
	s_cbranch_scc1 .Lfg_nl0
	s_waitcnt lgkmcnt(4)
	v_mfma_f32_32x32x16_f16 v[114:129], v[178:181], v[194:197], v[114:129]
	ds_read_b128 v[216:219], v131 offset:0
	s_waitcnt lgkmcnt(4)
	s_add_u32 m0, s18, 0x6000
	v_mfma_f32_32x32x16_f16 v[98:113], v[178:181], v[198:201], v[98:113]
	global_load_lds_dwordx4 v139, s[14:15]
	ds_read_b128 v[234:237], v133 offset:16384
	s_waitcnt lgkmcnt(4)
	s_add_u32 m0, s18, 0x7000
	v_mfma_f32_32x32x16_f16 v[82:97], v[182:185], v[194:197], v[82:97]
	global_load_lds_dwordx4 v140, s[14:15]
	ds_read_b128 v[240:243], v133 offset:18432
	s_add_u32 m0, s18, 0x8000
	v_mfma_f32_32x32x16_f16 v[66:81], v[182:185], v[198:201], v[66:81]
	global_load_lds_dwordx4 v141, s[14:15]
	ds_read_b128 v[220:223], v131 offset:2048
	s_waitcnt lgkmcnt(5)
	s_add_u32 m0, s18, 0x9000
	v_mfma_f32_32x32x16_f16 v[50:65], v[186:189], v[194:197], v[50:65]
	global_load_lds_dwordx4 v142, s[14:15]
	ds_read_b128 v[226:229], v131 offset:4096
	s_add_u32 m0, s18, 0xa000
	v_mfma_f32_32x32x16_f16 v[34:49], v[186:189], v[198:201], v[34:49]
	global_load_lds_dwordx4 v143, s[16:17]
	ds_read_b128 v[230:233], v131 offset:6144
	s_waitcnt lgkmcnt(6)
	s_add_u32 m0, s18, 0xb000
	v_mfma_f32_32x32x16_f16 v[18:33], v[190:193], v[194:197], v[18:33]
	global_load_lds_dwordx4 v144, s[16:17]
	v_mfma_f32_32x32x16_f16 v[2:17], v[190:193], v[198:201], v[2:17]
	s_add_u32 s14, s14, 64
	s_addc_u32 s15, s15, 0
	s_add_u32 s16, s16, 64
	s_addc_u32 s17, s17, 0
	s_branch .Lfg_dd0
.Lfg_nl0:
	s_waitcnt lgkmcnt(4)
	v_mfma_f32_32x32x16_f16 v[114:129], v[178:181], v[194:197], v[114:129]
	ds_read_b128 v[216:219], v131 offset:0
	s_waitcnt lgkmcnt(4)
	v_mfma_f32_32x32x16_f16 v[98:113], v[178:181], v[198:201], v[98:113]
	ds_read_b128 v[234:237], v133 offset:16384
	s_waitcnt lgkmcnt(4)
	v_mfma_f32_32x32x16_f16 v[82:97], v[182:185], v[194:197], v[82:97]
	ds_read_b128 v[240:243], v133 offset:18432
	v_mfma_f32_32x32x16_f16 v[66:81], v[182:185], v[198:201], v[66:81]
	ds_read_b128 v[220:223], v131 offset:2048
	s_waitcnt lgkmcnt(5)
	v_mfma_f32_32x32x16_f16 v[50:65], v[186:189], v[194:197], v[50:65]
	ds_read_b128 v[226:229], v131 offset:4096
	v_mfma_f32_32x32x16_f16 v[34:49], v[186:189], v[198:201], v[34:49]
	ds_read_b128 v[230:233], v131 offset:6144
	s_waitcnt lgkmcnt(6)
	v_mfma_f32_32x32x16_f16 v[18:33], v[190:193], v[194:197], v[18:33]
	v_mfma_f32_32x32x16_f16 v[2:17], v[190:193], v[198:201], v[2:17]

.Lfg_stage1:
	ds_read_b128 v[178:181], v130 offset:24576
	ds_read_b128 v[194:197], v132 offset:40960
	ds_read_b128 v[198:201], v132 offset:43008
	ds_read_b128 v[182:185], v130 offset:26624
	ds_read_b128 v[186:189], v130 offset:28672
	ds_read_b128 v[190:193], v130 offset:30720
	s_cmp_ge_u32 s13, 31
	s_cbranch_scc1 .Lfg_nl1
	s_waitcnt lgkmcnt(4)
	v_mfma_f32_32x32x16_f16 v[114:129], v[178:181], v[194:197], v[114:129]
	ds_read_b128 v[216:219], v131 offset:24576
	s_waitcnt lgkmcnt(4)
	s_add_u32 m0, s18, 0x0
	v_mfma_f32_32x32x16_f16 v[98:113], v[178:181], v[198:201], v[98:113]
	global_load_lds_dwordx4 v139, s[14:15]
	ds_read_b128 v[234:237], v133 offset:40960
	s_waitcnt lgkmcnt(4)
	s_add_u32 m0, s18, 0x1000
	v_mfma_f32_32x32x16_f16 v[82:97], v[182:185], v[194:197], v[82:97]
	global_load_lds_dwordx4 v140, s[14:15]
	ds_read_b128 v[240:243], v133 offset:43008
	s_add_u32 m0, s18, 0x2000
	v_mfma_f32_32x32x16_f16 v[66:81], v[182:185], v[198:201], v[66:81]
	global_load_lds_dwordx4 v141, s[14:15]
	ds_read_b128 v[220:223], v131 offset:26624
	s_waitcnt lgkmcnt(5)
	s_add_u32 m0, s18, 0x3000
	v_mfma_f32_32x32x16_f16 v[50:65], v[186:189], v[194:197], v[50:65]
	global_load_lds_dwordx4 v142, s[14:15]
	ds_read_b128 v[226:229], v131 offset:28672
	s_add_u32 m0, s18, 0x4000
	v_mfma_f32_32x32x16_f16 v[34:49], v[186:189], v[198:201], v[34:49]
	global_load_lds_dwordx4 v143, s[16:17]
	ds_read_b128 v[230:233], v131 offset:30720
	s_waitcnt lgkmcnt(6)
	s_add_u32 m0, s18, 0x5000
	v_mfma_f32_32x32x16_f16 v[18:33], v[190:193], v[194:197], v[18:33]
	global_load_lds_dwordx4 v144, s[16:17]
	v_mfma_f32_32x32x16_f16 v[2:17], v[190:193], v[198:201], v[2:17]
	s_add_u32 s14, s14, 64
	s_addc_u32 s15, s15, 0
	s_add_u32 s16, s16, 64
	s_addc_u32 s17, s17, 0
	s_branch .Lfg_dd1
.Lfg_nl1:
	s_waitcnt lgkmcnt(4)
	v_mfma_f32_32x32x16_f16 v[114:129], v[178:181], v[194:197], v[114:129]
	ds_read_b128 v[216:219], v131 offset:24576
	s_waitcnt lgkmcnt(4)
	v_mfma_f32_32x32x16_f16 v[98:113], v[178:181], v[198:201], v[98:113]
	ds_read_b128 v[234:237], v133 offset:40960
	s_waitcnt lgkmcnt(4)
	v_mfma_f32_32x32x16_f16 v[82:97], v[182:185], v[194:197], v[82:97]
	ds_read_b128 v[240:243], v133 offset:43008
	v_mfma_f32_32x32x16_f16 v[66:81], v[182:185], v[198:201], v[66:81]
	ds_read_b128 v[220:223], v131 offset:26624
	s_waitcnt lgkmcnt(5)
	v_mfma_f32_32x32x16_f16 v[50:65], v[186:189], v[194:197], v[50:65]
	ds_read_b128 v[226:229], v131 offset:28672
	v_mfma_f32_32x32x16_f16 v[34:49], v[186:189], v[198:201], v[34:49]
	ds_read_b128 v[230:233], v131 offset:30720
	s_waitcnt lgkmcnt(6)
	v_mfma_f32_32x32x16_f16 v[18:33], v[190:193], v[194:197], v[18:33]
	v_mfma_f32_32x32x16_f16 v[2:17], v[190:193], v[198:201], v[2:17]

.Lwo_stage0:
	ds_read_b128 v[66:69], v130 offset:0
	ds_read_b128 v[74:77], v134 offset:16384
	ds_read_b128 v[78:81], v134 offset:20480
	ds_read_b128 v[70:73], v130 offset:4096
	ds_read_b128 v[82:85], v131 offset:0
	ds_read_b128 v[90:93], v135 offset:16384
	ds_read_b128 v[94:97], v135 offset:20480
	ds_read_b128 v[86:89], v131 offset:4096
	s_cmp_ge_u32 s22, 15
	s_cbranch_scc1 .Lwo_nl0
	s_waitcnt lgkmcnt(6)
	s_add_u32 m0, s38, 0x8000
	v_mfma_f32_32x32x16_f16 v[50:65], v[66:69], v[74:77], v[50:65]
	global_load_lds_dwordx4 v152, s[10:11]
	ds_read_b128 v[98:101], v132 offset:0
	s_waitcnt lgkmcnt(6)
	s_add_u32 m0, s38, 0xc000
	v_mfma_f32_32x32x16_f16 v[34:49], v[66:69], v[78:81], v[34:49]
	global_load_lds_dwordx4 v152, s[8:9]
	ds_read_b128 v[106:109], v136 offset:16384
	s_waitcnt lgkmcnt(6)
	s_add_u32 m0, s38, 0x9000
	v_mfma_f32_32x32x16_f16 v[18:33], v[70:73], v[74:77], v[18:33]
	global_load_lds_dwordx4 v150, s[10:11]
	ds_read_b128 v[110:113], v136 offset:20480
	s_add_u32 m0, s38, 0xd000
	v_mfma_f32_32x32x16_f16 v[2:17], v[70:73], v[78:81], v[2:17]
	global_load_lds_dwordx4 v150, s[8:9]
	ds_read_b128 v[102:105], v132 offset:4096
	s_waitcnt lgkmcnt(6)
	s_add_u32 m0, s38, 0xa000
	v_mfma_f32_32x32x16_f16 v[50:65], v[82:85], v[90:93], v[50:65]
	global_load_lds_dwordx4 v148, s[10:11]
	ds_read_b128 v[114:117], v133 offset:0
	s_waitcnt lgkmcnt(6)
	s_add_u32 m0, s38, 0xe000
	v_mfma_f32_32x32x16_f16 v[34:49], v[82:85], v[94:97], v[34:49]
	global_load_lds_dwordx4 v148, s[8:9]
	ds_read_b128 v[122:125], v137 offset:16384
	s_waitcnt lgkmcnt(6)
	s_add_u32 m0, s38, 0xb000
	v_mfma_f32_32x32x16_f16 v[18:33], v[86:89], v[90:93], v[18:33]
	global_load_lds_dwordx4 v146, s[10:11]
	ds_read_b128 v[126:129], v137 offset:20480
	s_add_u32 m0, s38, 0xf000
	v_mfma_f32_32x32x16_f16 v[2:17], v[86:89], v[94:97], v[2:17]
	global_load_lds_dwordx4 v146, s[8:9]
	ds_read_b128 v[118:121], v133 offset:4096
	s_add_u32 s8, s8, 0x80
	s_addc_u32 s9, s9, 0
	s_add_u32 s10, s10, 0x80
	s_addc_u32 s11, s11, 0
	s_branch .Lwo_dd0

.Lwo_stage1:
	ds_read_b128 v[66:69], v130 offset:32768
	ds_read_b128 v[74:77], v134 offset:49152
	ds_read_b128 v[78:81], v134 offset:53248
	ds_read_b128 v[70:73], v130 offset:36864
	ds_read_b128 v[82:85], v131 offset:32768
	ds_read_b128 v[90:93], v135 offset:49152
	ds_read_b128 v[94:97], v135 offset:53248
	ds_read_b128 v[86:89], v131 offset:36864
	s_cmp_ge_u32 s22, 15
	s_cbranch_scc1 .Lwo_nl1
	s_waitcnt lgkmcnt(6)
	s_add_u32 m0, s38, 0x0
	v_mfma_f32_32x32x16_f16 v[50:65], v[66:69], v[74:77], v[50:65]
	global_load_lds_dwordx4 v152, s[10:11]
	ds_read_b128 v[98:101], v132 offset:32768
	s_waitcnt lgkmcnt(6)
	s_add_u32 m0, s38, 0x4000
	v_mfma_f32_32x32x16_f16 v[34:49], v[66:69], v[78:81], v[34:49]
	global_load_lds_dwordx4 v152, s[8:9]
	ds_read_b128 v[106:109], v136 offset:49152
	s_waitcnt lgkmcnt(6)
	s_add_u32 m0, s38, 0x1000
	v_mfma_f32_32x32x16_f16 v[18:33], v[70:73], v[74:77], v[18:33]
	global_load_lds_dwordx4 v150, s[10:11]
	ds_read_b128 v[110:113], v136 offset:53248
	s_add_u32 m0, s38, 0x5000
	v_mfma_f32_32x32x16_f16 v[2:17], v[70:73], v[78:81], v[2:17]
	global_load_lds_dwordx4 v150, s[8:9]
	ds_read_b128 v[102:105], v132 offset:36864
	s_waitcnt lgkmcnt(6)
	s_add_u32 m0, s38, 0x2000
	v_mfma_f32_32x32x16_f16 v[50:65], v[82:85], v[90:93], v[50:65]
	global_load_lds_dwordx4 v148, s[10:11]
	ds_read_b128 v[114:117], v133 offset:32768
	s_waitcnt lgkmcnt(6)
	s_add_u32 m0, s38, 0x6000
	v_mfma_f32_32x32x16_f16 v[34:49], v[82:85], v[94:97], v[34:49]
	global_load_lds_dwordx4 v148, s[8:9]
	ds_read_b128 v[122:125], v137 offset:49152
	s_waitcnt lgkmcnt(6)
	s_add_u32 m0, s38, 0x3000
	v_mfma_f32_32x32x16_f16 v[18:33], v[86:89], v[90:93], v[18:33]
	global_load_lds_dwordx4 v146, s[10:11]
	ds_read_b128 v[126:129], v137 offset:53248
	s_add_u32 m0, s38, 0x7000
	v_mfma_f32_32x32x16_f16 v[2:17], v[86:89], v[94:97], v[2:17]
	global_load_lds_dwordx4 v146, s[8:9]
	ds_read_b128 v[118:121], v133 offset:36864
	s_add_u32 s8, s8, 0x80
	s_addc_u32 s9, s9, 0
	s_add_u32 s10, s10, 0x80
	s_addc_u32 s11, s11, 0
	s_branch .Lwo_dd1

.Lpg_stage0:
	ds_read_b128 v[178:181], v130 offset:0
	ds_read_b128 v[194:197], v132 offset:16384
	ds_read_b128 v[198:201], v132 offset:18432
	ds_read_b128 v[182:185], v130 offset:2048
	ds_read_b128 v[186:189], v130 offset:4096
	ds_read_b128 v[190:193], v130 offset:6144
	s_cmp_ge_u32 s1, 31
	s_cbranch_scc1 .Lpg_nl0
	s_waitcnt lgkmcnt(4)
	v_mfma_f32_32x32x16_f16 v[114:129], v[178:181], v[194:197], v[114:129]
	ds_read_b128 v[216:219], v131 offset:0
	s_waitcnt lgkmcnt(4)
	s_add_u32 m0, s18, 0x6000
	v_mfma_f32_32x32x16_f16 v[98:113], v[178:181], v[198:201], v[98:113]
	global_load_lds_dwordx4 v139, s[4:5]
	ds_read_b128 v[234:237], v133 offset:16384
	s_waitcnt lgkmcnt(4)
	s_add_u32 m0, s18, 0x7000
	v_mfma_f32_32x32x16_f16 v[82:97], v[182:185], v[194:197], v[82:97]
	global_load_lds_dwordx4 v140, s[4:5]
	ds_read_b128 v[240:243], v133 offset:18432
	s_add_u32 m0, s18, 0x8000
	v_mfma_f32_32x32x16_f16 v[66:81], v[182:185], v[198:201], v[66:81]
	global_load_lds_dwordx4 v141, s[4:5]
	ds_read_b128 v[220:223], v131 offset:2048
	s_waitcnt lgkmcnt(5)
	s_add_u32 m0, s18, 0x9000
	v_mfma_f32_32x32x16_f16 v[50:65], v[186:189], v[194:197], v[50:65]
	global_load_lds_dwordx4 v142, s[4:5]
	ds_read_b128 v[226:229], v131 offset:4096
	s_add_u32 m0, s18, 0xa000
	v_mfma_f32_32x32x16_f16 v[34:49], v[186:189], v[198:201], v[34:49]
	global_load_lds_dwordx4 v143, s[6:7]
	ds_read_b128 v[230:233], v131 offset:6144
	s_waitcnt lgkmcnt(6)
	s_add_u32 m0, s18, 0xb000
	v_mfma_f32_32x32x16_f16 v[18:33], v[190:193], v[194:197], v[18:33]
	global_load_lds_dwordx4 v144, s[6:7]
	v_mfma_f32_32x32x16_f16 v[2:17], v[190:193], v[198:201], v[2:17]
	s_add_u32 s4, s4, 64
	s_addc_u32 s5, s5, 0
	s_add_u32 s6, s6, 64
	s_addc_u32 s7, s7, 0
	s_branch .Lpg_dd0

.Lpg_stage1:
	ds_read_b128 v[178:181], v130 offset:24576
	ds_read_b128 v[194:197], v132 offset:40960
	ds_read_b128 v[198:201], v132 offset:43008
	ds_read_b128 v[182:185], v130 offset:26624
	ds_read_b128 v[186:189], v130 offset:28672
	ds_read_b128 v[190:193], v130 offset:30720
	s_cmp_ge_u32 s1, 31
	s_cbranch_scc1 .Lpg_nl1
	s_waitcnt lgkmcnt(4)
	v_mfma_f32_32x32x16_f16 v[114:129], v[178:181], v[194:197], v[114:129]
	ds_read_b128 v[216:219], v131 offset:24576
	s_waitcnt lgkmcnt(4)
	s_add_u32 m0, s18, 0x0
	v_mfma_f32_32x32x16_f16 v[98:113], v[178:181], v[198:201], v[98:113]
	global_load_lds_dwordx4 v139, s[4:5]
	ds_read_b128 v[234:237], v133 offset:40960
	s_waitcnt lgkmcnt(4)
	s_add_u32 m0, s18, 0x1000
	v_mfma_f32_32x32x16_f16 v[82:97], v[182:185], v[194:197], v[82:97]
	global_load_lds_dwordx4 v140, s[4:5]
	ds_read_b128 v[240:243], v133 offset:43008
	s_add_u32 m0, s18, 0x2000
	v_mfma_f32_32x32x16_f16 v[66:81], v[182:185], v[198:201], v[66:81]
	global_load_lds_dwordx4 v141, s[4:5]
	ds_read_b128 v[220:223], v131 offset:26624
	s_waitcnt lgkmcnt(5)
	s_add_u32 m0, s18, 0x3000
	v_mfma_f32_32x32x16_f16 v[50:65], v[186:189], v[194:197], v[50:65]
	global_load_lds_dwordx4 v142, s[4:5]
	ds_read_b128 v[226:229], v131 offset:28672
	s_add_u32 m0, s18, 0x4000
	v_mfma_f32_32x32x16_f16 v[34:49], v[186:189], v[198:201], v[34:49]
	global_load_lds_dwordx4 v143, s[6:7]
	ds_read_b128 v[230:233], v131 offset:30720
	s_waitcnt lgkmcnt(6)
	s_add_u32 m0, s18, 0x5000
	v_mfma_f32_32x32x16_f16 v[18:33], v[190:193], v[194:197], v[18:33]
	global_load_lds_dwordx4 v144, s[6:7]
	v_mfma_f32_32x32x16_f16 v[2:17], v[190:193], v[198:201], v[2:17]
	s_add_u32 s4, s4, 64
	s_addc_u32 s5, s5, 0
	s_add_u32 s6, s6, 64
	s_addc_u32 s7, s7, 0
	s_branch .Lpg_dd1
